# P5 scan pass-1 step loop rewritten by hand: state in 4x4-block layout, rank-1/rank-2 updates on v_mfma_f32_4x4x1_16b_f32 (f32), dots on VALU with quad DPP reduce
# speedup vs baseline: 1.0067x; 1.0067x over previous
; #define LAS __attribute__((address_space(3)))
;     ...
;     const int tid = threadIdx.x, lane = tid & 63, wave = tid >> 6, G = gridDim.x;
;     const int gw = blockIdx.x * NWAVES + wave, NGW = G * NWAVES;
;     unsigned char* ws = p.ws;
;     const float* DEC = (const float*)(ws + WS_DEC);
;     const bf16* R = (const bf16*)p.out; const bf16* KF = R + (size_t)T * DB; const bf16* V = KF + (size_t)T * DB; const bf16* KKN = V + (size_t)T * DB; const bf16* Bv = (const bf16*)(ws + WS_B);
;     const bf16* Gt = (const bf16*)(ws + WS_G); const float* BON = (const float*)(ws + WS_BONUS); bf16* YB = (bf16*)(ws + WS_YB);
;     float* ST = (float*)(ws + WS_ST); float* YT = (float*)p.out; bf16* ZT = (bf16*)p.out + (size_t)3 * T * DB;
;     const bf16* FEAT = (const bf16*)(ws + WS_FEAT); const bf16* AS = (const bf16*)(ws + WS_AS); bf16* Vw = (bf16*)p.out + (size_t)2 * T * DB; float* BONw = (float*)(ws + WS_BONUS);
;     LAS float* buf = (LAS float*)(lds + wave * 16384);
;     for (int u = gw; u < 32 * NCH; u += NGW) {
;         const int bh = u / NCH, ch = u % NCH, b = bh >> 4, h = bh & 15; int lnl = lane; asm volatile("" : "+v"(lnl));
;         const unsigned i0 = (unsigned)((b * SEQ + ch * CL) * DB + h * 64) + (unsigned)lnl;
;         const unsigned q0 = (unsigned)((b * SEQ + ch * CL) * NH + h);
;         const unsigned f0 = (unsigned)((b * SEQ + ch * CL) * 3072 + h * 64) + (unsigned)lnl;
;         const int cc_ = h * 64 + lnl;
;         const float mur = p.in[I_MU][cc_], muk = p.in[I_MU][1024 + cc_], muv = p.in[I_MU][2048 + cc_], ckk = p.in[I_KK][cc_], cka = p.in[I_KA][cc_], crk = p.in[I_RK][cc_];
;     ...
;         if (!PASS2 && MODE == 0) { f32x4* sq = (f32x4*)(ST + ((size_t)u * 2) * 4096 + lane * 64); f32x4* sp = (f32x4*)(ST + ((size_t)u * 2 + 1) * 4096 + lane * 64);
; #pragma unroll
;             for (int j = 0; j < 16; ++j) { sq[j] = (f32x4){Q2[2 * j].x, Q2[2 * j].y, Q2[2 * j + 1].x, Q2[2 * j + 1].y}; sp[j] = (f32x4){P2[2 * j].x, P2[2 * j].y, P2[2 * j + 1].x, P2[2 * j + 1].y}; } }
.LBB0_1048:
	s_cmp_lt_i32 s30, 6
	s_cselect_b64 s[0:1], -1, 0
	s_cmp_gt_i32 s31, 5
	s_cselect_b64 s[4:5], -1, 0
	s_and_b64 s[4:5], s[0:1], s[4:5]
	s_andn2_b64 vcc, exec, s[4:5]
	s_cbranch_vccnz .LBB0_1080
	v_lshl_add_u32 v128, s96, 3, v145
	s_movk_i32 s3, 0x800
	v_cmp_gt_i32_e32 vcc, s3, v128
	s_and_saveexec_b64 s[6:7], vcc
	s_cbranch_execz .LBB0_1079
	v_readlane_b32 s4, v244, 0
	s_lshl_b32 s3, s4, 3
	s_add_u32 s8, s28, 0x10800000
	s_addc_u32 s9, s29, 0
	s_add_u32 s10, s28, 0x38000000
	s_addc_u32 s11, s29, 0
	s_add_u32 s12, s26, 0xc000000
	s_addc_u32 s13, s27, 0
	s_add_u32 s14, s28, 0x18800000
	s_addc_u32 s15, s29, 0
	s_add_u32 s16, s28, 0x28000000
	s_addc_u32 s17, s29, 0
	s_add_u32 s18, s26, 0x8000000
	v_and_b32_e32 v147, 63, v144
	s_addc_u32 s19, s27, 0
	v_readlane_b32 s5, v244, 1
	s_add_u32 s36, s28, 0x8500000
	v_lshl_add_u32 v151, v145, 14, 0
	v_lshlrev_b32_e32 v155, 2, v147
	s_waitcnt lgkmcnt(0)
	v_and_b32_e32 v1, 15, v144
	v_lshlrev_b32_e32 v0, 6, v147
	s_addc_u32 s37, s29, 0
	v_add_u32_e32 v180, v151, v155
	v_cmp_eq_u32_e64 s[4:5], 0, v147
	v_mov_b32_e32 v131, 0
	v_lshlrev_b32_e32 v181, 2, v1
	s_mov_b64 s[38:39], 0
	s_movk_i32 s33, 0x1000
	s_movk_i32 s40, 0x1800
	s_movk_i32 s41, 0x7fff
	v_lshlrev_b32_e32 v132, 2, v0
	s_mov_b64 s[52:53], 0x4000
	s_movk_i32 s42, 0x7ff
	v_and_b32_e32 v246, 3, v147
	v_and_b32_e32 v245, 60, v147
	v_lshl_or_b32 v245, v246, 6, v245
	v_add_u32_e32 v180, v151, v245
	s_mov_b32 s98, 0x22222222
	s_mov_b32 s99, 0x22222222
	s_mov_b32 s100, 0x44444444
	s_mov_b32 s101, 0x44444444
	s_mov_b32 s84, 0x88888888
	s_mov_b32 s85, 0x88888888
	s_branch .LBB0_1052
.LBB0_1051:
	v_lshlrev_b64 v[134:135], 15, v[128:129]
	v_lshl_add_u64 v[134:135], s[10:11], 0, v[134:135]
	v_and_b32_e32 v130, 60, v147
	v_lshlrev_b32_e32 v130, 8, v130
	v_and_b32_e32 v136, 3, v147
	v_lshl_or_b32 v130, v136, 2, v130
	v_lshl_add_u64 v[134:135], v[134:135], 0, v[130:131]
	v_lshl_add_u64 v[136:137], v[134:135], 0, s[52:53]
	global_store_dword v[134:135], v0, off offset:0
	global_store_dword v[134:135], v1, off offset:256
	global_store_dword v[134:135], v2, off offset:512
	global_store_dword v[134:135], v3, off offset:768
	global_store_dword v[134:135], v4, off offset:16
	global_store_dword v[134:135], v5, off offset:272
	global_store_dword v[134:135], v6, off offset:528
	global_store_dword v[134:135], v7, off offset:784
	global_store_dword v[134:135], v8, off offset:32
	global_store_dword v[134:135], v9, off offset:288
	global_store_dword v[134:135], v10, off offset:544
	global_store_dword v[134:135], v11, off offset:800
	global_store_dword v[134:135], v12, off offset:48
	global_store_dword v[134:135], v13, off offset:304
	global_store_dword v[134:135], v14, off offset:560
	global_store_dword v[134:135], v15, off offset:816
	global_store_dword v[134:135], v16, off offset:64
	global_store_dword v[134:135], v17, off offset:320
	global_store_dword v[134:135], v18, off offset:576
	global_store_dword v[134:135], v19, off offset:832
	global_store_dword v[134:135], v20, off offset:80
	global_store_dword v[134:135], v21, off offset:336
	global_store_dword v[134:135], v22, off offset:592
	global_store_dword v[134:135], v23, off offset:848
	global_store_dword v[134:135], v24, off offset:96
	global_store_dword v[134:135], v25, off offset:352
	global_store_dword v[134:135], v26, off offset:608
	global_store_dword v[134:135], v27, off offset:864
	global_store_dword v[134:135], v28, off offset:112
	global_store_dword v[134:135], v29, off offset:368
	global_store_dword v[134:135], v30, off offset:624
	global_store_dword v[134:135], v31, off offset:880
	global_store_dword v[134:135], v32, off offset:128
	global_store_dword v[134:135], v33, off offset:384
	global_store_dword v[134:135], v34, off offset:640
	global_store_dword v[134:135], v35, off offset:896
	global_store_dword v[134:135], v36, off offset:144
	global_store_dword v[134:135], v37, off offset:400
	global_store_dword v[134:135], v38, off offset:656
	global_store_dword v[134:135], v39, off offset:912
	global_store_dword v[134:135], v40, off offset:160
	global_store_dword v[134:135], v41, off offset:416
	global_store_dword v[134:135], v42, off offset:672
	global_store_dword v[134:135], v43, off offset:928
	global_store_dword v[134:135], v44, off offset:176
	global_store_dword v[134:135], v45, off offset:432
	global_store_dword v[134:135], v46, off offset:688
;     ...
;         if (!PASS2 && MODE == 0) { f32x4* sq = (f32x4*)(ST + ((size_t)u * 2) * 4096 + lane * 64); f32x4* sp = (f32x4*)(ST + ((size_t)u * 2 + 1) * 4096 + lane * 64);
; #pragma unroll
;             for (int j = 0; j < 16; ++j) { sq[j] = (f32x4){Q2[2 * j].x, Q2[2 * j].y, Q2[2 * j + 1].x, Q2[2 * j + 1].y}; sp[j] = (f32x4){P2[2 * j].x, P2[2 * j].y, P2[2 * j + 1].x, P2[2 * j + 1].y}; } }
	global_store_dword v[134:135], v47, off offset:944
	global_store_dword v[134:135], v48, off offset:192
	global_store_dword v[134:135], v49, off offset:448
	global_store_dword v[134:135], v50, off offset:704
	global_store_dword v[134:135], v51, off offset:960
	global_store_dword v[134:135], v52, off offset:208
	global_store_dword v[134:135], v53, off offset:464
	global_store_dword v[134:135], v54, off offset:720
	global_store_dword v[134:135], v55, off offset:976
	global_store_dword v[134:135], v56, off offset:224
	global_store_dword v[134:135], v57, off offset:480
	global_store_dword v[134:135], v58, off offset:736
	global_store_dword v[134:135], v59, off offset:992
	global_store_dword v[134:135], v60, off offset:240
	global_store_dword v[134:135], v61, off offset:496
	global_store_dword v[134:135], v62, off offset:752
	global_store_dword v[134:135], v63, off offset:1008
	global_store_dword v[136:137], v64, off offset:0
	global_store_dword v[136:137], v65, off offset:256
	global_store_dword v[136:137], v66, off offset:512
	global_store_dword v[136:137], v67, off offset:768
	global_store_dword v[136:137], v68, off offset:16
	global_store_dword v[136:137], v69, off offset:272
	global_store_dword v[136:137], v70, off offset:528
	global_store_dword v[136:137], v71, off offset:784
	global_store_dword v[136:137], v72, off offset:32
	global_store_dword v[136:137], v73, off offset:288
	global_store_dword v[136:137], v74, off offset:544
	global_store_dword v[136:137], v75, off offset:800
	global_store_dword v[136:137], v76, off offset:48
	global_store_dword v[136:137], v77, off offset:304
	global_store_dword v[136:137], v78, off offset:560
	global_store_dword v[136:137], v79, off offset:816
	global_store_dword v[136:137], v80, off offset:64
	global_store_dword v[136:137], v81, off offset:320
	global_store_dword v[136:137], v82, off offset:576
	global_store_dword v[136:137], v83, off offset:832
	global_store_dword v[136:137], v84, off offset:80
	global_store_dword v[136:137], v85, off offset:336
	global_store_dword v[136:137], v86, off offset:592
	global_store_dword v[136:137], v87, off offset:848
	global_store_dword v[136:137], v88, off offset:96
	global_store_dword v[136:137], v89, off offset:352
	global_store_dword v[136:137], v90, off offset:608
	global_store_dword v[136:137], v91, off offset:864
	global_store_dword v[136:137], v92, off offset:112
	global_store_dword v[136:137], v93, off offset:368
	global_store_dword v[136:137], v94, off offset:624
	global_store_dword v[136:137], v95, off offset:880
	global_store_dword v[136:137], v96, off offset:128
	global_store_dword v[136:137], v97, off offset:384
	global_store_dword v[136:137], v98, off offset:640
	global_store_dword v[136:137], v99, off offset:896
	global_store_dword v[136:137], v100, off offset:144
	global_store_dword v[136:137], v101, off offset:400
	global_store_dword v[136:137], v102, off offset:656
	global_store_dword v[136:137], v103, off offset:912
	global_store_dword v[136:137], v104, off offset:160
	global_store_dword v[136:137], v105, off offset:416
	global_store_dword v[136:137], v106, off offset:672
	global_store_dword v[136:137], v107, off offset:928
	global_store_dword v[136:137], v108, off offset:176
	global_store_dword v[136:137], v109, off offset:432
	global_store_dword v[136:137], v110, off offset:688
	global_store_dword v[136:137], v111, off offset:944
	global_store_dword v[136:137], v112, off offset:192
	global_store_dword v[136:137], v113, off offset:448
	global_store_dword v[136:137], v114, off offset:704
	global_store_dword v[136:137], v115, off offset:960
	global_store_dword v[136:137], v116, off offset:208
	global_store_dword v[136:137], v117, off offset:464
	global_store_dword v[136:137], v118, off offset:720
	global_store_dword v[136:137], v119, off offset:976
	global_store_dword v[136:137], v120, off offset:224
	global_store_dword v[136:137], v121, off offset:480
	global_store_dword v[136:137], v122, off offset:736
	global_store_dword v[136:137], v123, off offset:992
	global_store_dword v[136:137], v124, off offset:240
	global_store_dword v[136:137], v125, off offset:496
	global_store_dword v[136:137], v126, off offset:752
	global_store_dword v[136:137], v127, off offset:1008
	v_add_u32_e32 v128, s3, v128
	v_cmp_lt_i32_e32 vcc, s42, v128
	s_or_b64 s[38:39], vcc, s[38:39]
	s_andn2_b64 exec, exec, s[38:39]
	s_cbranch_execz .LBB0_1079

;     ...
;         f32x2 Q2[32], P2[32];
; #pragma unroll
;         for (int k = 0; k < 32; ++k) { Q2[k] = (f32x2){0.f, 0.f}; P2[k] = (f32x2){(2 * k == lnl) ? 1.f : 0.f, (2 * k + 1 == lnl) ? 1.f : 0.f}; }
.LBB0_1062:
	s_or_b64 exec, exec, s[64:65]
	v_cmp_eq_u32_e32 vcc, 0, v65
	v_lshlrev_b32_e32 v67, 20, v64
	v_and_b32_e32 v67, 0xff000000, v67
	v_cndmask_b32_e64 v0, 0, 1.0, vcc
	v_cmp_eq_u32_e32 vcc, 1, v65
	v_lshlrev_b32_e32 v64, 24, v64
	v_mov_b32_e32 v130, v131
	v_cndmask_b32_e64 v1, 0, 1.0, vcc
	v_cmp_eq_u32_e32 vcc, 2, v65
	s_mov_b32 s43, 0
	s_mov_b64 s[64:65], 0
	v_cndmask_b32_e64 v2, 0, 1.0, vcc
	v_cmp_eq_u32_e32 vcc, 3, v65
	v_mov_b64_e32 v[70:71], v[130:131]
	v_mov_b64_e32 v[68:69], v[130:131]
	v_cndmask_b32_e64 v3, 0, 1.0, vcc
	v_cmp_eq_u32_e32 vcc, 4, v65
	v_mov_b64_e32 v[74:75], v[130:131]
	v_mov_b64_e32 v[72:73], v[130:131]
	v_cndmask_b32_e64 v4, 0, 1.0, vcc
	v_cmp_eq_u32_e32 vcc, 5, v65
	v_mov_b64_e32 v[78:79], v[130:131]
	v_mov_b64_e32 v[76:77], v[130:131]
	v_cndmask_b32_e64 v5, 0, 1.0, vcc
	v_cmp_eq_u32_e32 vcc, 6, v65
	v_mov_b64_e32 v[86:87], v[130:131]
	v_mov_b64_e32 v[84:85], v[130:131]
	v_cndmask_b32_e64 v6, 0, 1.0, vcc
	v_cmp_eq_u32_e32 vcc, 7, v65
	v_mov_b64_e32 v[94:95], v[130:131]
	v_mov_b64_e32 v[92:93], v[130:131]
	v_cndmask_b32_e64 v7, 0, 1.0, vcc
	v_cmp_eq_u32_e32 vcc, 8, v65
	v_mov_b64_e32 v[98:99], v[130:131]
	v_mov_b64_e32 v[96:97], v[130:131]
	v_cndmask_b32_e64 v8, 0, 1.0, vcc
	v_cmp_eq_u32_e32 vcc, 9, v65
	v_mov_b64_e32 v[102:103], v[130:131]
	v_mov_b64_e32 v[100:101], v[130:131]
	v_cndmask_b32_e64 v9, 0, 1.0, vcc
	v_cmp_eq_u32_e32 vcc, 10, v65
	v_mov_b64_e32 v[106:107], v[130:131]
	v_mov_b64_e32 v[104:105], v[130:131]
	v_cndmask_b32_e64 v10, 0, 1.0, vcc
	v_cmp_eq_u32_e32 vcc, 11, v65
	v_mov_b64_e32 v[110:111], v[130:131]
	v_mov_b64_e32 v[108:109], v[130:131]
	v_cndmask_b32_e64 v11, 0, 1.0, vcc
	v_cmp_eq_u32_e32 vcc, 12, v65
	v_mov_b64_e32 v[114:115], v[130:131]
	v_mov_b64_e32 v[112:113], v[130:131]
	v_cndmask_b32_e64 v12, 0, 1.0, vcc
	v_cmp_eq_u32_e32 vcc, 13, v65
	v_mov_b64_e32 v[118:119], v[130:131]
	v_mov_b64_e32 v[116:117], v[130:131]
	v_cndmask_b32_e64 v13, 0, 1.0, vcc
	v_cmp_eq_u32_e32 vcc, 14, v65
	v_mov_b64_e32 v[122:123], v[130:131]
	v_mov_b64_e32 v[120:121], v[130:131]
	v_cndmask_b32_e64 v14, 0, 1.0, vcc
	v_cmp_eq_u32_e32 vcc, 15, v65
	v_mov_b64_e32 v[126:127], v[130:131]
	v_mov_b64_e32 v[124:125], v[130:131]
	v_cndmask_b32_e64 v15, 0, 1.0, vcc
	v_cmp_eq_u32_e32 vcc, 16, v65
	v_mov_b64_e32 v[88:89], v[130:131]
	v_mov_b64_e32 v[90:91], v[130:131]
	v_cndmask_b32_e64 v16, 0, 1.0, vcc
	v_cmp_eq_u32_e32 vcc, 17, v65
	v_mov_b64_e32 v[80:81], v[130:131]
	v_mov_b64_e32 v[82:83], v[130:131]
	v_cndmask_b32_e64 v17, 0, 1.0, vcc
	v_cmp_eq_u32_e32 vcc, 18, v65
	v_mov_b64_e32 v[160:161], v[156:157]
	v_mov_b64_e32 v[162:163], v[158:159]
	v_cndmask_b32_e64 v18, 0, 1.0, vcc
	v_cmp_eq_u32_e32 vcc, 19, v65
	s_nop 1
	v_cndmask_b32_e64 v19, 0, 1.0, vcc
	v_cmp_eq_u32_e32 vcc, 20, v65
	s_nop 1
	v_cndmask_b32_e64 v20, 0, 1.0, vcc
	v_cmp_eq_u32_e32 vcc, 21, v65
	s_nop 1
	v_cndmask_b32_e64 v21, 0, 1.0, vcc
	v_cmp_eq_u32_e32 vcc, 22, v65
	s_nop 1
	v_cndmask_b32_e64 v22, 0, 1.0, vcc
	v_cmp_eq_u32_e32 vcc, 23, v65
	s_nop 1
	v_cndmask_b32_e64 v23, 0, 1.0, vcc
	v_cmp_eq_u32_e32 vcc, 24, v65
	s_nop 1
	v_cndmask_b32_e64 v24, 0, 1.0, vcc
	v_cmp_eq_u32_e32 vcc, 25, v65
	s_nop 1
	v_cndmask_b32_e64 v25, 0, 1.0, vcc
	v_cmp_eq_u32_e32 vcc, 26, v65
	s_nop 1
	v_cndmask_b32_e64 v26, 0, 1.0, vcc
	v_cmp_eq_u32_e32 vcc, 27, v65
	s_nop 1
	v_cndmask_b32_e64 v27, 0, 1.0, vcc
	v_cmp_eq_u32_e32 vcc, 28, v65
	s_nop 1
	v_cndmask_b32_e64 v28, 0, 1.0, vcc
	v_cmp_eq_u32_e32 vcc, 29, v65
	s_nop 1
	v_cndmask_b32_e64 v29, 0, 1.0, vcc
	v_cmp_eq_u32_e32 vcc, 30, v65
	s_nop 1
	v_cndmask_b32_e64 v30, 0, 1.0, vcc
	v_cmp_eq_u32_e32 vcc, 31, v65
	s_nop 1
	v_cndmask_b32_e64 v31, 0, 1.0, vcc
	v_cmp_eq_u32_e32 vcc, 32, v65
	s_nop 1
	v_cndmask_b32_e64 v32, 0, 1.0, vcc
	v_cmp_eq_u32_e32 vcc, 33, v65
	s_nop 1
	v_cndmask_b32_e64 v33, 0, 1.0, vcc
	v_cmp_eq_u32_e32 vcc, 34, v65
	s_nop 1
	v_cndmask_b32_e64 v34, 0, 1.0, vcc
	v_cmp_eq_u32_e32 vcc, 35, v65
	s_nop 1
	v_cndmask_b32_e64 v35, 0, 1.0, vcc
	v_cmp_eq_u32_e32 vcc, 36, v65
	s_nop 1
	v_cndmask_b32_e64 v36, 0, 1.0, vcc
	v_cmp_eq_u32_e32 vcc, 37, v65
	s_nop 1
	v_cndmask_b32_e64 v37, 0, 1.0, vcc
	v_cmp_eq_u32_e32 vcc, 38, v65
	s_nop 1
	v_cndmask_b32_e64 v38, 0, 1.0, vcc
	v_cmp_eq_u32_e32 vcc, 39, v65
	s_nop 1
	v_cndmask_b32_e64 v39, 0, 1.0, vcc
	v_cmp_eq_u32_e32 vcc, 40, v65
	s_nop 1
	v_cndmask_b32_e64 v40, 0, 1.0, vcc
	v_cmp_eq_u32_e32 vcc, 41, v65
	s_nop 1
	v_cndmask_b32_e64 v41, 0, 1.0, vcc
	v_cmp_eq_u32_e32 vcc, 42, v65
	s_nop 1
	v_cndmask_b32_e64 v42, 0, 1.0, vcc
	v_cmp_eq_u32_e32 vcc, 43, v65
	s_nop 1
	v_cndmask_b32_e64 v43, 0, 1.0, vcc
	v_cmp_eq_u32_e32 vcc, 44, v65
	s_nop 1
	v_cndmask_b32_e64 v44, 0, 1.0, vcc
	v_cmp_eq_u32_e32 vcc, 45, v65
	s_nop 1
	v_cndmask_b32_e64 v45, 0, 1.0, vcc
	v_cmp_eq_u32_e32 vcc, 46, v65
	s_nop 1
	v_cndmask_b32_e64 v46, 0, 1.0, vcc
	v_cmp_eq_u32_e32 vcc, 47, v65
	s_nop 1
	v_cndmask_b32_e64 v47, 0, 1.0, vcc
	v_cmp_eq_u32_e32 vcc, 48, v65
	s_nop 1
	v_cndmask_b32_e64 v48, 0, 1.0, vcc
	v_cmp_eq_u32_e32 vcc, 49, v65
	s_nop 1
	v_cndmask_b32_e64 v49, 0, 1.0, vcc
	v_cmp_eq_u32_e32 vcc, 50, v65
	s_nop 1
	v_cndmask_b32_e64 v50, 0, 1.0, vcc
	v_cmp_eq_u32_e32 vcc, 51, v65
	s_nop 1
	v_cndmask_b32_e64 v51, 0, 1.0, vcc
	v_cmp_eq_u32_e32 vcc, 52, v65
	s_nop 1
	v_cndmask_b32_e64 v52, 0, 1.0, vcc
	v_cmp_eq_u32_e32 vcc, 53, v65
	s_nop 1
	v_cndmask_b32_e64 v53, 0, 1.0, vcc
	v_cmp_eq_u32_e32 vcc, 54, v65
	s_nop 1
	v_cndmask_b32_e64 v54, 0, 1.0, vcc
	v_cmp_eq_u32_e32 vcc, 55, v65
	s_nop 1
	v_cndmask_b32_e64 v55, 0, 1.0, vcc
	v_cmp_eq_u32_e32 vcc, 56, v65
	s_nop 1
	v_cndmask_b32_e64 v60, 0, 1.0, vcc
	v_cmp_eq_u32_e32 vcc, 57, v65
	s_nop 1
	v_cndmask_b32_e64 v61, 0, 1.0, vcc
	v_cmp_eq_u32_e32 vcc, 58, v65
;     ...
;         f32x2 Q2[32], P2[32];
; #pragma unroll
;         for (int k = 0; k < 32; ++k) { Q2[k] = (f32x2){0.f, 0.f}; P2[k] = (f32x2){(2 * k == lnl) ? 1.f : 0.f, (2 * k + 1 == lnl) ? 1.f : 0.f}; }
	s_nop 1
	v_cndmask_b32_e64 v62, 0, 1.0, vcc
	v_cmp_eq_u32_e32 vcc, 59, v65
	s_nop 1
	v_cndmask_b32_e64 v63, 0, 1.0, vcc
	v_cmp_eq_u32_e32 vcc, 60, v65
	s_nop 1
	v_cndmask_b32_e64 v56, 0, 1.0, vcc
	v_cmp_eq_u32_e32 vcc, 61, v65
	s_nop 1
	v_cndmask_b32_e64 v57, 0, 1.0, vcc
	v_cmp_eq_u32_e32 vcc, 62, v65
	s_nop 1
	v_cndmask_b32_e64 v58, 0, 1.0, vcc
	v_cmp_eq_u32_e32 vcc, 63, v65
	v_add_u32_e32 v65, v65, v67
	v_lshlrev_b32_e32 v67, 18, v128
	v_add3_u32 v65, v65, v67, v66
	v_cndmask_b32_e64 v59, 0, 1.0, vcc
	v_sub_u32_e32 v141, v65, v64
	v_mov_b64_e32 v[66:67], v[130:131]
	v_mov_b64_e32 v[64:65], v[130:131]
	v_mov_b32_e32 v0, 0
	v_mov_b32_e32 v1, 0
	v_mov_b32_e32 v2, 0
	v_mov_b32_e32 v3, 0
	v_mov_b32_e32 v4, 0
	v_mov_b32_e32 v5, 0
	v_mov_b32_e32 v6, 0
	v_mov_b32_e32 v7, 0
	v_mov_b32_e32 v8, 0
	v_mov_b32_e32 v9, 0
	v_mov_b32_e32 v10, 0
	v_mov_b32_e32 v11, 0
	v_mov_b32_e32 v12, 0
	v_mov_b32_e32 v13, 0
	v_mov_b32_e32 v14, 0
	v_mov_b32_e32 v15, 0
	v_mov_b32_e32 v16, 0
	v_mov_b32_e32 v17, 0
	v_mov_b32_e32 v18, 0
	v_mov_b32_e32 v19, 0
	v_mov_b32_e32 v20, 0
	v_mov_b32_e32 v21, 0
	v_mov_b32_e32 v22, 0
	v_mov_b32_e32 v23, 0
	v_mov_b32_e32 v24, 0
	v_mov_b32_e32 v25, 0
	v_mov_b32_e32 v26, 0
	v_mov_b32_e32 v27, 0
	v_mov_b32_e32 v28, 0
	v_mov_b32_e32 v29, 0
	v_mov_b32_e32 v30, 0
	v_mov_b32_e32 v31, 0
	v_mov_b32_e32 v32, 0
	v_mov_b32_e32 v33, 0
	v_mov_b32_e32 v34, 0
	v_mov_b32_e32 v35, 0
	v_mov_b32_e32 v36, 0
	v_mov_b32_e32 v37, 0
	v_mov_b32_e32 v38, 0
	v_mov_b32_e32 v39, 0
	v_mov_b32_e32 v40, 0
	v_mov_b32_e32 v41, 0
	v_mov_b32_e32 v42, 0
	v_mov_b32_e32 v43, 0
	v_mov_b32_e32 v44, 0
	v_mov_b32_e32 v45, 0
	v_mov_b32_e32 v46, 0
	v_mov_b32_e32 v47, 0
	v_mov_b32_e32 v48, 0
	v_mov_b32_e32 v49, 0
	v_mov_b32_e32 v50, 0
	v_mov_b32_e32 v51, 0
	v_mov_b32_e32 v52, 0
	v_mov_b32_e32 v53, 0
	v_mov_b32_e32 v54, 0
	v_mov_b32_e32 v55, 0
	v_mov_b32_e32 v56, 0
	v_mov_b32_e32 v57, 0
	v_mov_b32_e32 v58, 0
	v_mov_b32_e32 v59, 0
	v_mov_b32_e32 v60, 0
	v_mov_b32_e32 v61, 0
	v_mov_b32_e32 v62, 0
	v_mov_b32_e32 v63, 0
	v_cmp_eq_u32_e32 vcc, 0, v147
	s_nop 1
	v_cndmask_b32_e64 v64, 0, 1.0, vcc
	v_cmp_eq_u32_e32 vcc, 1, v147
	s_nop 1
	v_cndmask_b32_e64 v65, 0, 1.0, vcc
	v_cmp_eq_u32_e32 vcc, 2, v147
	s_nop 1
	v_cndmask_b32_e64 v66, 0, 1.0, vcc
	v_cmp_eq_u32_e32 vcc, 3, v147
	s_nop 1
	v_cndmask_b32_e64 v67, 0, 1.0, vcc
	v_cmp_eq_u32_e32 vcc, 4, v147
	s_nop 1
	v_cndmask_b32_e64 v68, 0, 1.0, vcc
	v_cmp_eq_u32_e32 vcc, 5, v147
	s_nop 1
	v_cndmask_b32_e64 v69, 0, 1.0, vcc
	v_cmp_eq_u32_e32 vcc, 6, v147
	s_nop 1
	v_cndmask_b32_e64 v70, 0, 1.0, vcc
	v_cmp_eq_u32_e32 vcc, 7, v147
	s_nop 1
	v_cndmask_b32_e64 v71, 0, 1.0, vcc
	v_cmp_eq_u32_e32 vcc, 8, v147
	s_nop 1
	v_cndmask_b32_e64 v72, 0, 1.0, vcc
	v_cmp_eq_u32_e32 vcc, 9, v147
	s_nop 1
	v_cndmask_b32_e64 v73, 0, 1.0, vcc
	v_cmp_eq_u32_e32 vcc, 10, v147
	s_nop 1
	v_cndmask_b32_e64 v74, 0, 1.0, vcc
	v_cmp_eq_u32_e32 vcc, 11, v147
	s_nop 1
	v_cndmask_b32_e64 v75, 0, 1.0, vcc
	v_cmp_eq_u32_e32 vcc, 12, v147
	s_nop 1
	v_cndmask_b32_e64 v76, 0, 1.0, vcc
	v_cmp_eq_u32_e32 vcc, 13, v147
	s_nop 1
	v_cndmask_b32_e64 v77, 0, 1.0, vcc
	v_cmp_eq_u32_e32 vcc, 14, v147
	s_nop 1
	v_cndmask_b32_e64 v78, 0, 1.0, vcc
	v_cmp_eq_u32_e32 vcc, 15, v147
	s_nop 1
	v_cndmask_b32_e64 v79, 0, 1.0, vcc
	v_cmp_eq_u32_e32 vcc, 16, v147
	s_nop 1
	v_cndmask_b32_e64 v80, 0, 1.0, vcc
	v_cmp_eq_u32_e32 vcc, 17, v147
	s_nop 1
	v_cndmask_b32_e64 v81, 0, 1.0, vcc
	v_cmp_eq_u32_e32 vcc, 18, v147
	s_nop 1
	v_cndmask_b32_e64 v82, 0, 1.0, vcc
	v_cmp_eq_u32_e32 vcc, 19, v147
	s_nop 1
	v_cndmask_b32_e64 v83, 0, 1.0, vcc
	v_cmp_eq_u32_e32 vcc, 20, v147
	s_nop 1
	v_cndmask_b32_e64 v84, 0, 1.0, vcc
	v_cmp_eq_u32_e32 vcc, 21, v147
	s_nop 1
	v_cndmask_b32_e64 v85, 0, 1.0, vcc
	v_cmp_eq_u32_e32 vcc, 22, v147
	s_nop 1
	v_cndmask_b32_e64 v86, 0, 1.0, vcc
	v_cmp_eq_u32_e32 vcc, 23, v147
	s_nop 1
	v_cndmask_b32_e64 v87, 0, 1.0, vcc
	v_cmp_eq_u32_e32 vcc, 24, v147
	s_nop 1
	v_cndmask_b32_e64 v88, 0, 1.0, vcc
	v_cmp_eq_u32_e32 vcc, 25, v147
	s_nop 1
	v_cndmask_b32_e64 v89, 0, 1.0, vcc
	v_cmp_eq_u32_e32 vcc, 26, v147
	s_nop 1
	v_cndmask_b32_e64 v90, 0, 1.0, vcc
	v_cmp_eq_u32_e32 vcc, 27, v147
	s_nop 1
	v_cndmask_b32_e64 v91, 0, 1.0, vcc
	v_cmp_eq_u32_e32 vcc, 28, v147
	s_nop 1
	v_cndmask_b32_e64 v92, 0, 1.0, vcc
	v_cmp_eq_u32_e32 vcc, 29, v147
	s_nop 1
	v_cndmask_b32_e64 v93, 0, 1.0, vcc
	v_cmp_eq_u32_e32 vcc, 30, v147
	s_nop 1
	v_cndmask_b32_e64 v94, 0, 1.0, vcc
	v_cmp_eq_u32_e32 vcc, 31, v147
	s_nop 1
	v_cndmask_b32_e64 v95, 0, 1.0, vcc
	v_cmp_eq_u32_e32 vcc, 32, v147
	s_nop 1
	v_cndmask_b32_e64 v96, 0, 1.0, vcc
	v_cmp_eq_u32_e32 vcc, 33, v147
	s_nop 1
	v_cndmask_b32_e64 v97, 0, 1.0, vcc
	v_cmp_eq_u32_e32 vcc, 34, v147
	s_nop 1
	v_cndmask_b32_e64 v98, 0, 1.0, vcc
	v_cmp_eq_u32_e32 vcc, 35, v147
	s_nop 1
	v_cndmask_b32_e64 v99, 0, 1.0, vcc
	v_cmp_eq_u32_e32 vcc, 36, v147
	s_nop 1
	v_cndmask_b32_e64 v100, 0, 1.0, vcc
	v_cmp_eq_u32_e32 vcc, 37, v147
	s_nop 1
	v_cndmask_b32_e64 v101, 0, 1.0, vcc
	v_cmp_eq_u32_e32 vcc, 38, v147
	s_nop 1
	v_cndmask_b32_e64 v102, 0, 1.0, vcc
	v_cmp_eq_u32_e32 vcc, 39, v147
	s_nop 1
	v_cndmask_b32_e64 v103, 0, 1.0, vcc
	v_cmp_eq_u32_e32 vcc, 40, v147
	s_nop 1
	v_cndmask_b32_e64 v104, 0, 1.0, vcc
	v_cmp_eq_u32_e32 vcc, 41, v147
	s_nop 1
	v_cndmask_b32_e64 v105, 0, 1.0, vcc
	v_cmp_eq_u32_e32 vcc, 42, v147
	s_nop 1
	v_cndmask_b32_e64 v106, 0, 1.0, vcc
	v_cmp_eq_u32_e32 vcc, 43, v147
	s_nop 1
	v_cndmask_b32_e64 v107, 0, 1.0, vcc
	v_cmp_eq_u32_e32 vcc, 44, v147
	s_nop 1
	v_cndmask_b32_e64 v108, 0, 1.0, vcc
	v_cmp_eq_u32_e32 vcc, 45, v147
	s_nop 1
	v_cndmask_b32_e64 v109, 0, 1.0, vcc
	v_cmp_eq_u32_e32 vcc, 46, v147
	s_nop 1
	v_cndmask_b32_e64 v110, 0, 1.0, vcc
	v_cmp_eq_u32_e32 vcc, 47, v147
	s_nop 1
	v_cndmask_b32_e64 v111, 0, 1.0, vcc
	v_cmp_eq_u32_e32 vcc, 48, v147
	s_nop 1
	v_cndmask_b32_e64 v112, 0, 1.0, vcc
	v_cmp_eq_u32_e32 vcc, 49, v147
	s_nop 1
	v_cndmask_b32_e64 v113, 0, 1.0, vcc
	v_cmp_eq_u32_e32 vcc, 50, v147
	s_nop 1
	v_cndmask_b32_e64 v114, 0, 1.0, vcc
	v_cmp_eq_u32_e32 vcc, 51, v147
	s_nop 1
	v_cndmask_b32_e64 v115, 0, 1.0, vcc
	v_cmp_eq_u32_e32 vcc, 52, v147
	s_nop 1
	v_cndmask_b32_e64 v116, 0, 1.0, vcc
	v_cmp_eq_u32_e32 vcc, 53, v147
	s_nop 1
	v_cndmask_b32_e64 v117, 0, 1.0, vcc
	v_cmp_eq_u32_e32 vcc, 54, v147
	s_nop 1
	v_cndmask_b32_e64 v118, 0, 1.0, vcc
	v_cmp_eq_u32_e32 vcc, 55, v147
	s_nop 1
	v_cndmask_b32_e64 v119, 0, 1.0, vcc
	v_cmp_eq_u32_e32 vcc, 56, v147
	s_nop 1
	v_cndmask_b32_e64 v120, 0, 1.0, vcc
	v_cmp_eq_u32_e32 vcc, 57, v147
	s_nop 1
	v_cndmask_b32_e64 v121, 0, 1.0, vcc
	v_cmp_eq_u32_e32 vcc, 58, v147
	s_nop 1
	v_cndmask_b32_e64 v122, 0, 1.0, vcc
	v_cmp_eq_u32_e32 vcc, 59, v147
	s_nop 1
	v_cndmask_b32_e64 v123, 0, 1.0, vcc
	v_cmp_eq_u32_e32 vcc, 60, v147
	s_nop 1
	v_cndmask_b32_e64 v124, 0, 1.0, vcc
	v_cmp_eq_u32_e32 vcc, 61, v147
	s_nop 1
	v_cndmask_b32_e64 v125, 0, 1.0, vcc
	v_cmp_eq_u32_e32 vcc, 62, v147
	s_nop 1
	v_cndmask_b32_e64 v126, 0, 1.0, vcc
	v_cmp_eq_u32_e32 vcc, 63, v147
	s_nop 1
	v_cndmask_b32_e64 v127, 0, 1.0, vcc

;     ...
;                 DPPFMAC(qd0, xkq0, Q2[0].x, 0); DPPFMAC(pd0, xkq0, P2[0].x, 0);
;                 DPPFMAC(qd1, xkq0, Q2[0].y, 1); DPPFMAC(pd1, xkq0, P2[0].y, 1);
;                 DPPFMAC(qd2, xkq0, Q2[1].x, 2); DPPFMAC(pd2, xkq0, P2[1].x, 2);
;                 DPPFMAC(qd3, xkq0, Q2[1].y, 3); DPPFMAC(pd3, xkq0, P2[1].y, 3);
;                 DPPFMAC(qd0, xkq0, Q2[2].x, 4); DPPFMAC(pd0, xkq0, P2[2].x, 4);
;                 DPPFMAC(qd1, xkq0, Q2[2].y, 5); DPPFMAC(pd1, xkq0, P2[2].y, 5);
;                 DPPFMAC(qd2, xkq0, Q2[3].x, 6); DPPFMAC(pd2, xkq0, P2[3].x, 6);
;                 DPPFMAC(qd3, xkq0, Q2[3].y, 7); DPPFMAC(pd3, xkq0, P2[3].y, 7);
;                 DPPFMAC(qd0, xkq0, Q2[4].x, 8); DPPFMAC(pd0, xkq0, P2[4].x, 8);
;                 DPPFMAC(qd1, xkq0, Q2[4].y, 9); DPPFMAC(pd1, xkq0, P2[4].y, 9);
;                 DPPFMAC(qd2, xkq0, Q2[5].x, 10); DPPFMAC(pd2, xkq0, P2[5].x, 10);
;                 DPPFMAC(qd3, xkq0, Q2[5].y, 11); DPPFMAC(pd3, xkq0, P2[5].y, 11);
;                 DPPFMAC(qd0, xkq0, Q2[6].x, 12); DPPFMAC(pd0, xkq0, P2[6].x, 12);
;                 DPPFMAC(qd1, xkq0, Q2[6].y, 13); DPPFMAC(pd1, xkq0, P2[6].y, 13);
;                 DPPFMAC(qd2, xkq0, Q2[7].x, 14); DPPFMAC(pd2, xkq0, P2[7].x, 14);
;                 DPPFMAC(qd3, xkq0, Q2[7].y, 15); DPPFMAC(pd3, xkq0, P2[7].y, 15);
;                 __builtin_amdgcn_sched_barrier(0);
;                 DPPFMAC(qd0, xkq1, Q2[8].x, 0); DPPFMAC(pd0, xkq1, P2[8].x, 0);
;                 DPPFMAC(qd1, xkq1, Q2[8].y, 1); DPPFMAC(pd1, xkq1, P2[8].y, 1);
;                 DPPFMAC(qd2, xkq1, Q2[9].x, 2); DPPFMAC(pd2, xkq1, P2[9].x, 2);
;                 DPPFMAC(qd3, xkq1, Q2[9].y, 3); DPPFMAC(pd3, xkq1, P2[9].y, 3);
;                 DPPFMAC(qd0, xkq1, Q2[10].x, 4); DPPFMAC(pd0, xkq1, P2[10].x, 4);
;                 DPPFMAC(qd1, xkq1, Q2[10].y, 5); DPPFMAC(pd1, xkq1, P2[10].y, 5);
;                 DPPFMAC(qd2, xkq1, Q2[11].x, 6); DPPFMAC(pd2, xkq1, P2[11].x, 6);
;                 DPPFMAC(qd3, xkq1, Q2[11].y, 7); DPPFMAC(pd3, xkq1, P2[11].y, 7);
;                 DPPFMAC(qd0, xkq1, Q2[12].x, 8); DPPFMAC(pd0, xkq1, P2[12].x, 8);
;                 DPPFMAC(qd1, xkq1, Q2[12].y, 9); DPPFMAC(pd1, xkq1, P2[12].y, 9);
;                 DPPFMAC(qd2, xkq1, Q2[13].x, 10); DPPFMAC(pd2, xkq1, P2[13].x, 10);
;                 DPPFMAC(qd3, xkq1, Q2[13].y, 11); DPPFMAC(pd3, xkq1, P2[13].y, 11);
.Lp5_step:
	v_and_b32_e32 v255, 0xc0, v245
	v_add_u32_e32 v255, v255, v158
	v_add_u32_e32 v130, v245, v158
	ds_read_b128 v[192:195], v255 offset:256
	ds_read_b128 v[196:199], v255 offset:272
	ds_read_b128 v[200:203], v255 offset:288
	ds_read_b128 v[204:207], v255 offset:304
	ds_read_b32 v254, v130 offset:1024
	ds_read_b128 v[208:211], v255 offset:0
	ds_read_b128 v[212:215], v255 offset:16
	ds_read_b128 v[216:219], v255 offset:32
	ds_read_b128 v[220:223], v255 offset:48
	ds_read_b128 v[224:227], v255 offset:512
	ds_read_b128 v[228:231], v255 offset:528
	ds_read_b128 v[232:235], v255 offset:544
	ds_read_b128 v[236:239], v255 offset:560
	s_waitcnt lgkmcnt(9)
	ds_read_b128 v[240:243], v255 offset:768
	ds_read_b128 v[166:169], v255 offset:784
	ds_read_b128 v[170:173], v255 offset:800
	ds_read_b128 v[174:177], v255 offset:816
	v_mul_f32_e32 v246, v0, v192
	v_mul_f32_e32 v250, v64, v192
	v_mul_f32_e32 v247, v1, v192
	v_mul_f32_e32 v251, v65, v192
	v_mul_f32_e32 v248, v2, v192
	v_mul_f32_e32 v252, v66, v192
	v_mul_f32_e32 v249, v3, v192
	v_mul_f32_e32 v253, v67, v192
	v_fmac_f32_e32 v246, v4, v193
	v_fmac_f32_e32 v250, v68, v193
	v_fmac_f32_e32 v247, v5, v193
	v_fmac_f32_e32 v251, v69, v193
	v_fmac_f32_e32 v248, v6, v193
	v_fmac_f32_e32 v252, v70, v193
	v_fmac_f32_e32 v249, v7, v193
	v_fmac_f32_e32 v253, v71, v193
	v_fmac_f32_e32 v246, v8, v194
	v_fmac_f32_e32 v250, v72, v194
	v_fmac_f32_e32 v247, v9, v194
	v_fmac_f32_e32 v251, v73, v194
	v_fmac_f32_e32 v248, v10, v194
	v_fmac_f32_e32 v252, v74, v194
	v_fmac_f32_e32 v249, v11, v194
	v_fmac_f32_e32 v253, v75, v194
	v_fmac_f32_e32 v246, v12, v195
	v_fmac_f32_e32 v250, v76, v195
	v_fmac_f32_e32 v247, v13, v195
	v_fmac_f32_e32 v251, v77, v195
	v_fmac_f32_e32 v248, v14, v195
	v_fmac_f32_e32 v252, v78, v195
	v_fmac_f32_e32 v249, v15, v195
	v_fmac_f32_e32 v253, v79, v195
	v_fmac_f32_e32 v246, v16, v196
	v_fmac_f32_e32 v250, v80, v196
	v_fmac_f32_e32 v247, v17, v196
	v_fmac_f32_e32 v251, v81, v196
	v_fmac_f32_e32 v248, v18, v196
	v_fmac_f32_e32 v252, v82, v196
	v_fmac_f32_e32 v249, v19, v196
	v_fmac_f32_e32 v253, v83, v196
	v_fmac_f32_e32 v246, v20, v197
	v_fmac_f32_e32 v250, v84, v197
	v_fmac_f32_e32 v247, v21, v197
	v_fmac_f32_e32 v251, v85, v197
	v_fmac_f32_e32 v248, v22, v197
	v_fmac_f32_e32 v252, v86, v197
	v_fmac_f32_e32 v249, v23, v197
	v_fmac_f32_e32 v253, v87, v197
	v_fmac_f32_e32 v246, v24, v198
	v_fmac_f32_e32 v250, v88, v198
	v_fmac_f32_e32 v247, v25, v198
	v_fmac_f32_e32 v251, v89, v198
	v_fmac_f32_e32 v248, v26, v198
	v_fmac_f32_e32 v252, v90, v198
	v_fmac_f32_e32 v249, v27, v198
	v_fmac_f32_e32 v253, v91, v198
	v_fmac_f32_e32 v246, v28, v199
	v_fmac_f32_e32 v250, v92, v199
	v_fmac_f32_e32 v247, v29, v199
	v_fmac_f32_e32 v251, v93, v199
	v_fmac_f32_e32 v248, v30, v199
	v_fmac_f32_e32 v252, v94, v199
	v_fmac_f32_e32 v249, v31, v199
	v_fmac_f32_e32 v253, v95, v199
	v_fmac_f32_e32 v246, v32, v200
	v_fmac_f32_e32 v250, v96, v200
	v_fmac_f32_e32 v247, v33, v200
	v_fmac_f32_e32 v251, v97, v200
	v_fmac_f32_e32 v248, v34, v200
	v_fmac_f32_e32 v252, v98, v200
	v_fmac_f32_e32 v249, v35, v200
	v_fmac_f32_e32 v253, v99, v200
	v_fmac_f32_e32 v246, v36, v201
	v_fmac_f32_e32 v250, v100, v201
	v_fmac_f32_e32 v247, v37, v201
	v_fmac_f32_e32 v251, v101, v201
	v_fmac_f32_e32 v248, v38, v201
	v_fmac_f32_e32 v252, v102, v201
	v_fmac_f32_e32 v249, v39, v201
	v_fmac_f32_e32 v253, v103, v201
	v_fmac_f32_e32 v246, v40, v202
	v_fmac_f32_e32 v250, v104, v202
	v_fmac_f32_e32 v247, v41, v202
	v_fmac_f32_e32 v251, v105, v202
	v_fmac_f32_e32 v248, v42, v202
	v_fmac_f32_e32 v252, v106, v202
	v_fmac_f32_e32 v249, v43, v202
	v_fmac_f32_e32 v253, v107, v202
	v_fmac_f32_e32 v246, v44, v203
	v_fmac_f32_e32 v250, v108, v203
	v_fmac_f32_e32 v247, v45, v203
	v_fmac_f32_e32 v251, v109, v203
	v_fmac_f32_e32 v248, v46, v203
	v_fmac_f32_e32 v252, v110, v203
	v_fmac_f32_e32 v249, v47, v203
	v_fmac_f32_e32 v253, v111, v203
	v_fmac_f32_e32 v246, v48, v204
	v_fmac_f32_e32 v250, v112, v204
	v_fmac_f32_e32 v247, v49, v204
	v_fmac_f32_e32 v251, v113, v204
	v_fmac_f32_e32 v248, v50, v204
	v_fmac_f32_e32 v252, v114, v204
	v_fmac_f32_e32 v249, v51, v204
	v_fmac_f32_e32 v253, v115, v204
	v_fmac_f32_e32 v246, v52, v205
	v_fmac_f32_e32 v250, v116, v205
	v_fmac_f32_e32 v247, v53, v205
	v_fmac_f32_e32 v251, v117, v205
	v_fmac_f32_e32 v248, v54, v205
	v_fmac_f32_e32 v252, v118, v205
	v_fmac_f32_e32 v249, v55, v205
	v_fmac_f32_e32 v253, v119, v205
	v_fmac_f32_e32 v246, v56, v206
	v_fmac_f32_e32 v250, v120, v206
	v_fmac_f32_e32 v247, v57, v206
	v_fmac_f32_e32 v251, v121, v206
	v_fmac_f32_e32 v248, v58, v206
	v_fmac_f32_e32 v252, v122, v206
	v_fmac_f32_e32 v249, v59, v206
	v_fmac_f32_e32 v253, v123, v206
	v_fmac_f32_e32 v246, v60, v207
	v_fmac_f32_e32 v250, v124, v207
	v_fmac_f32_e32 v247, v61, v207
	v_fmac_f32_e32 v251, v125, v207
	v_fmac_f32_e32 v248, v62, v207
	v_fmac_f32_e32 v252, v126, v207
	v_fmac_f32_e32 v249, v63, v207
	v_fmac_f32_e32 v253, v127, v207
	v_add_f32_dpp v246, v246, v246 quad_perm:[1,0,3,2] row_mask:0xf bank_mask:0xf
	v_add_f32_dpp v247, v247, v247 quad_perm:[1,0,3,2] row_mask:0xf bank_mask:0xf
	v_add_f32_dpp v248, v248, v248 quad_perm:[1,0,3,2] row_mask:0xf bank_mask:0xf
	v_add_f32_dpp v249, v249, v249 quad_perm:[1,0,3,2] row_mask:0xf bank_mask:0xf
	v_add_f32_dpp v250, v250, v250 quad_perm:[1,0,3,2] row_mask:0xf bank_mask:0xf
	v_add_f32_dpp v251, v251, v251 quad_perm:[1,0,3,2] row_mask:0xf bank_mask:0xf
	v_add_f32_dpp v252, v252, v252 quad_perm:[1,0,3,2] row_mask:0xf bank_mask:0xf
	v_add_f32_dpp v253, v253, v253 quad_perm:[1,0,3,2] row_mask:0xf bank_mask:0xf
	v_add_f32_dpp v246, v246, v246 quad_perm:[2,3,0,1] row_mask:0xf bank_mask:0xf
	v_add_f32_dpp v247, v247, v247 quad_perm:[2,3,0,1] row_mask:0xf bank_mask:0xf
	v_add_f32_dpp v248, v248, v248 quad_perm:[2,3,0,1] row_mask:0xf bank_mask:0xf
	v_add_f32_dpp v249, v249, v249 quad_perm:[2,3,0,1] row_mask:0xf bank_mask:0xf
	v_add_f32_dpp v250, v250, v250 quad_perm:[2,3,0,1] row_mask:0xf bank_mask:0xf
	v_add_f32_dpp v251, v251, v251 quad_perm:[2,3,0,1] row_mask:0xf bank_mask:0xf
	v_add_f32_dpp v252, v252, v252 quad_perm:[2,3,0,1] row_mask:0xf bank_mask:0xf
	v_add_f32_dpp v253, v253, v253 quad_perm:[2,3,0,1] row_mask:0xf bank_mask:0xf
	v_cndmask_b32_e64 v178, -v246, -v247, s[98:99]
	v_cndmask_b32_e64 v179, -v250, -v251, s[98:99]
	v_cndmask_b32_e64 v178, v178, -v248, s[100:101]
	v_cndmask_b32_e64 v179, v179, -v252, s[100:101]
	v_cndmask_b32_e64 v178, v178, -v249, s[84:85]
	v_cndmask_b32_e64 v179, v179, -v253, s[84:85]
	s_waitcnt lgkmcnt(0)
;     ...
;                 { const f32x2 bxy = b_0.xy, bzw = b_0.zw;
;                 Q2[0] = Q2[0] * d_0.xy + (saq2 * bxy + vv2 * k_0.xy); Q2[1] = Q2[1] * d_0.zw + (saq2 * bzw + vv2 * k_0.zw);
;                 P2[0] = P2[0] * d_0.xy + sap2 * bxy; P2[1] = P2[1] * d_0.zw + sap2 * bzw;
;                 DPPFMAC(yd0, xrq0, Q2[0].x, 0); DPPFMAC(zd0, xrq0, P2[0].x, 0);
;                 DPPFMAC(yd1, xrq0, Q2[0].y, 1); DPPFMAC(zd1, xrq0, P2[0].y, 1);
;                 DPPFMAC(yd2, xrq0, Q2[1].x, 2); DPPFMAC(zd2, xrq0, P2[1].x, 2);
;                 DPPFMAC(yd3, xrq0, Q2[1].y, 3); DPPFMAC(zd3, xrq0, P2[1].y, 3);
;                 }
;                 { const f32x2 bxy = b_1.xy, bzw = b_1.zw;
;                 Q2[2] = Q2[2] * d_1.xy + (saq2 * bxy + vv2 * k_1.xy); Q2[3] = Q2[3] * d_1.zw + (saq2 * bzw + vv2 * k_1.zw);
;                 P2[2] = P2[2] * d_1.xy + sap2 * bxy; P2[3] = P2[3] * d_1.zw + sap2 * bzw;
;                 DPPFMAC(yd0, xrq0, Q2[2].x, 4); DPPFMAC(zd0, xrq0, P2[2].x, 4);
;                 DPPFMAC(yd1, xrq0, Q2[2].y, 5); DPPFMAC(zd1, xrq0, P2[2].y, 5);
;                 DPPFMAC(yd2, xrq0, Q2[3].x, 6); DPPFMAC(zd2, xrq0, P2[3].x, 6);
;                 DPPFMAC(yd3, xrq0, Q2[3].y, 7); DPPFMAC(zd3, xrq0, P2[3].y, 7);
;                 }
;                 __builtin_amdgcn_sched_barrier(0);
;                 f32x4 d_4 = L4[4], b_4 = L4[36], k_4 = L4[52];
;                 f32x4 d_5 = L4[5], b_5 = L4[37], k_5 = L4[53];
;                 { const f32x2 bxy = b_2.xy, bzw = b_2.zw;
;                 Q2[4] = Q2[4] * d_2.xy + (saq2 * bxy + vv2 * k_2.xy); Q2[5] = Q2[5] * d_2.zw + (saq2 * bzw + vv2 * k_2.zw);
;                 P2[4] = P2[4] * d_2.xy + sap2 * bxy; P2[5] = P2[5] * d_2.zw + sap2 * bzw;
;                 DPPFMAC(yd0, xrq0, Q2[4].x, 8); DPPFMAC(zd0, xrq0, P2[4].x, 8);
;                 DPPFMAC(yd1, xrq0, Q2[4].y, 9); DPPFMAC(zd1, xrq0, P2[4].y, 9);
;                 DPPFMAC(yd2, xrq0, Q2[5].x, 10); DPPFMAC(zd2, xrq0, P2[5].x, 10);
;                 DPPFMAC(yd3, xrq0, Q2[5].y, 11); DPPFMAC(zd3, xrq0, P2[5].y, 11);
;                 }
;                 { const f32x2 bxy = b_3.xy, bzw = b_3.zw;
;                 Q2[6] = Q2[6] * d_3.xy + (saq2 * bxy + vv2 * k_3.xy); Q2[7] = Q2[7] * d_3.zw + (saq2 * bzw + vv2 * k_3.zw);
;                 P2[6] = P2[6] * d_3.xy + sap2 * bxy; P2[7] = P2[7] * d_3.zw + sap2 * bzw;
	ds_read_b128 v[192:195], v255 offset:1280
	ds_read_b128 v[196:199], v255 offset:1296
	ds_read_b128 v[200:203], v255 offset:1312
	ds_read_b128 v[204:207], v255 offset:1328
	v_mul_f32_e32 v0, v0, v208
	v_mul_f32_e32 v1, v1, v208
	v_mul_f32_e32 v2, v2, v208
	v_mul_f32_e32 v3, v3, v208
	v_mul_f32_e32 v64, v64, v208
	v_mul_f32_e32 v65, v65, v208
	v_mul_f32_e32 v66, v66, v208
	v_mul_f32_e32 v67, v67, v208
	v_mfma_f32_4x4x1_16b_f32 v[0:3], v178, v224, v[0:3]
	v_mul_f32_e32 v4, v4, v209
	v_mul_f32_e32 v5, v5, v209
	v_mul_f32_e32 v6, v6, v209
	v_mul_f32_e32 v7, v7, v209
	v_mfma_f32_4x4x1_16b_f32 v[64:67], v179, v224, v[64:67]
	v_mul_f32_e32 v68, v68, v209
	v_mul_f32_e32 v69, v69, v209
	v_mul_f32_e32 v70, v70, v209
	v_mul_f32_e32 v71, v71, v209
	v_mfma_f32_4x4x1_16b_f32 v[0:3], v254, v240, v[0:3]
	v_mfma_f32_4x4x1_16b_f32 v[4:7], v178, v225, v[4:7]
	v_mul_f32_e32 v8, v8, v210
	v_mul_f32_e32 v9, v9, v210
	v_mul_f32_e32 v10, v10, v210
	v_mul_f32_e32 v11, v11, v210
	v_mfma_f32_4x4x1_16b_f32 v[68:71], v179, v225, v[68:71]
	v_mul_f32_e32 v72, v72, v210
	v_mul_f32_e32 v73, v73, v210
	v_mul_f32_e32 v74, v74, v210
	v_mul_f32_e32 v75, v75, v210
	v_mfma_f32_4x4x1_16b_f32 v[4:7], v254, v241, v[4:7]
	s_waitcnt lgkmcnt(0)
	v_mul_f32_e32 v246, v0, v192
	v_mul_f32_e32 v250, v64, v192
	v_mul_f32_e32 v247, v1, v192
	v_mul_f32_e32 v251, v65, v192
	v_mul_f32_e32 v248, v2, v192
	v_mul_f32_e32 v252, v66, v192
	v_mul_f32_e32 v249, v3, v192
	v_mul_f32_e32 v253, v67, v192
	v_mfma_f32_4x4x1_16b_f32 v[8:11], v178, v226, v[8:11]
	v_mul_f32_e32 v12, v12, v211
	v_mul_f32_e32 v13, v13, v211
	v_mul_f32_e32 v14, v14, v211
	v_mul_f32_e32 v15, v15, v211
	v_mfma_f32_4x4x1_16b_f32 v[72:75], v179, v226, v[72:75]
	v_mul_f32_e32 v76, v76, v211
	v_mul_f32_e32 v77, v77, v211
	v_mul_f32_e32 v78, v78, v211
	v_mul_f32_e32 v79, v79, v211
	v_mfma_f32_4x4x1_16b_f32 v[8:11], v254, v242, v[8:11]
	v_fmac_f32_e32 v246, v4, v193
	v_fmac_f32_e32 v250, v68, v193
	v_fmac_f32_e32 v247, v5, v193
	v_fmac_f32_e32 v251, v69, v193
	v_fmac_f32_e32 v248, v6, v193
	v_fmac_f32_e32 v252, v70, v193
	v_fmac_f32_e32 v249, v7, v193
	v_fmac_f32_e32 v253, v71, v193
	v_mfma_f32_4x4x1_16b_f32 v[12:15], v178, v227, v[12:15]
	v_mul_f32_e32 v16, v16, v212
	v_mul_f32_e32 v17, v17, v212
	v_mul_f32_e32 v18, v18, v212
	v_mul_f32_e32 v19, v19, v212
	v_mfma_f32_4x4x1_16b_f32 v[76:79], v179, v227, v[76:79]
	v_mul_f32_e32 v80, v80, v212
	v_mul_f32_e32 v81, v81, v212
	v_mul_f32_e32 v82, v82, v212
	v_mul_f32_e32 v83, v83, v212
	v_mfma_f32_4x4x1_16b_f32 v[12:15], v254, v243, v[12:15]
	v_fmac_f32_e32 v246, v8, v194
	v_fmac_f32_e32 v250, v72, v194
	v_fmac_f32_e32 v247, v9, v194
	v_fmac_f32_e32 v251, v73, v194
	v_fmac_f32_e32 v248, v10, v194
	v_fmac_f32_e32 v252, v74, v194
	v_fmac_f32_e32 v249, v11, v194
	v_fmac_f32_e32 v253, v75, v194
	v_mfma_f32_4x4x1_16b_f32 v[16:19], v178, v228, v[16:19]
	v_mul_f32_e32 v20, v20, v213
	v_mul_f32_e32 v21, v21, v213
	v_mul_f32_e32 v22, v22, v213
	v_mul_f32_e32 v23, v23, v213
	v_mfma_f32_4x4x1_16b_f32 v[80:83], v179, v228, v[80:83]
	v_mul_f32_e32 v84, v84, v213
	v_mul_f32_e32 v85, v85, v213
	v_mul_f32_e32 v86, v86, v213
	v_mul_f32_e32 v87, v87, v213
	v_mfma_f32_4x4x1_16b_f32 v[16:19], v254, v166, v[16:19]
	v_fmac_f32_e32 v246, v12, v195
	v_fmac_f32_e32 v250, v76, v195
	v_fmac_f32_e32 v247, v13, v195
	v_fmac_f32_e32 v251, v77, v195
	v_fmac_f32_e32 v248, v14, v195
	v_fmac_f32_e32 v252, v78, v195
	v_fmac_f32_e32 v249, v15, v195
	v_fmac_f32_e32 v253, v79, v195
	v_mfma_f32_4x4x1_16b_f32 v[20:23], v178, v229, v[20:23]
	v_mul_f32_e32 v24, v24, v214
	v_mul_f32_e32 v25, v25, v214
	v_mul_f32_e32 v26, v26, v214
	v_mul_f32_e32 v27, v27, v214
	v_mfma_f32_4x4x1_16b_f32 v[84:87], v179, v229, v[84:87]
	v_mul_f32_e32 v88, v88, v214
	v_mul_f32_e32 v89, v89, v214
	v_mul_f32_e32 v90, v90, v214
	v_mul_f32_e32 v91, v91, v214
	v_mfma_f32_4x4x1_16b_f32 v[20:23], v254, v167, v[20:23]
	v_fmac_f32_e32 v246, v16, v196
	v_fmac_f32_e32 v250, v80, v196
	v_fmac_f32_e32 v247, v17, v196
	v_fmac_f32_e32 v251, v81, v196
	v_fmac_f32_e32 v248, v18, v196
	v_fmac_f32_e32 v252, v82, v196
	v_fmac_f32_e32 v249, v19, v196
	v_fmac_f32_e32 v253, v83, v196
	v_mfma_f32_4x4x1_16b_f32 v[24:27], v178, v230, v[24:27]
	v_mul_f32_e32 v28, v28, v215
	v_mul_f32_e32 v29, v29, v215
	v_mul_f32_e32 v30, v30, v215
	v_mul_f32_e32 v31, v31, v215
	v_mfma_f32_4x4x1_16b_f32 v[88:91], v179, v230, v[88:91]
	v_mul_f32_e32 v92, v92, v215
	v_mul_f32_e32 v93, v93, v215
	v_mul_f32_e32 v94, v94, v215
	v_mul_f32_e32 v95, v95, v215
	v_mfma_f32_4x4x1_16b_f32 v[24:27], v254, v168, v[24:27]
	v_fmac_f32_e32 v246, v20, v197
	v_fmac_f32_e32 v250, v84, v197
	v_fmac_f32_e32 v247, v21, v197
	v_fmac_f32_e32 v251, v85, v197
	v_fmac_f32_e32 v248, v22, v197
	v_fmac_f32_e32 v252, v86, v197
	v_fmac_f32_e32 v249, v23, v197
	v_fmac_f32_e32 v253, v87, v197
	v_mfma_f32_4x4x1_16b_f32 v[28:31], v178, v231, v[28:31]
	v_mul_f32_e32 v32, v32, v216
	v_mul_f32_e32 v33, v33, v216
	v_mul_f32_e32 v34, v34, v216
	v_mul_f32_e32 v35, v35, v216
	v_mfma_f32_4x4x1_16b_f32 v[92:95], v179, v231, v[92:95]
	v_mul_f32_e32 v96, v96, v216
	v_mul_f32_e32 v97, v97, v216
	v_mul_f32_e32 v98, v98, v216
	v_mul_f32_e32 v99, v99, v216
	v_mfma_f32_4x4x1_16b_f32 v[28:31], v254, v169, v[28:31]
	v_fmac_f32_e32 v246, v24, v198
	v_fmac_f32_e32 v250, v88, v198
	v_fmac_f32_e32 v247, v25, v198
	v_fmac_f32_e32 v251, v89, v198
	v_fmac_f32_e32 v248, v26, v198
	v_fmac_f32_e32 v252, v90, v198
	v_fmac_f32_e32 v249, v27, v198
	v_fmac_f32_e32 v253, v91, v198
	v_mfma_f32_4x4x1_16b_f32 v[32:35], v178, v232, v[32:35]
	v_mul_f32_e32 v36, v36, v217
	v_mul_f32_e32 v37, v37, v217
	v_mul_f32_e32 v38, v38, v217
	v_mul_f32_e32 v39, v39, v217
;     ...
;                 { const f32x2 bxy = b_8.xy, bzw = b_8.zw;
;                 Q2[16] = Q2[16] * d_8.xy + (saq2 * bxy + vv2 * k_8.xy); Q2[17] = Q2[17] * d_8.zw + (saq2 * bzw + vv2 * k_8.zw);
;                 P2[16] = P2[16] * d_8.xy + sap2 * bxy; P2[17] = P2[17] * d_8.zw + sap2 * bzw;
;                 DPPFMAC(yd0, xrq2, Q2[16].x, 0); DPPFMAC(zd0, xrq2, P2[16].x, 0);
;                 DPPFMAC(yd1, xrq2, Q2[16].y, 1); DPPFMAC(zd1, xrq2, P2[16].y, 1);
;                 DPPFMAC(yd2, xrq2, Q2[17].x, 2); DPPFMAC(zd2, xrq2, P2[17].x, 2);
;                 DPPFMAC(yd3, xrq2, Q2[17].y, 3); DPPFMAC(zd3, xrq2, P2[17].y, 3);
;                 }
;                 { const f32x2 bxy = b_9.xy, bzw = b_9.zw;
;                 Q2[18] = Q2[18] * d_9.xy + (saq2 * bxy + vv2 * k_9.xy); Q2[19] = Q2[19] * d_9.zw + (saq2 * bzw + vv2 * k_9.zw);
;                 P2[18] = P2[18] * d_9.xy + sap2 * bxy; P2[19] = P2[19] * d_9.zw + sap2 * bzw;
;                 DPPFMAC(yd0, xrq2, Q2[18].x, 4); DPPFMAC(zd0, xrq2, P2[18].x, 4);
;                 DPPFMAC(yd1, xrq2, Q2[18].y, 5); DPPFMAC(zd1, xrq2, P2[18].y, 5);
;                 DPPFMAC(yd2, xrq2, Q2[19].x, 6); DPPFMAC(zd2, xrq2, P2[19].x, 6);
;                 DPPFMAC(yd3, xrq2, Q2[19].y, 7); DPPFMAC(zd3, xrq2, P2[19].y, 7);
;                 }
;                 __builtin_amdgcn_sched_barrier(0);
;                 f32x4 d_12 = L4[12], b_12 = L4[44], k_12 = L4[60];
;                 f32x4 d_13 = L4[13], b_13 = L4[45], k_13 = L4[61];
;                 { const f32x2 bxy = b_10.xy, bzw = b_10.zw;
;                 Q2[20] = Q2[20] * d_10.xy + (saq2 * bxy + vv2 * k_10.xy); Q2[21] = Q2[21] * d_10.zw + (saq2 * bzw + vv2 * k_10.zw);
;                 P2[20] = P2[20] * d_10.xy + sap2 * bxy; P2[21] = P2[21] * d_10.zw + sap2 * bzw;
;                 DPPFMAC(yd0, xrq2, Q2[20].x, 8); DPPFMAC(zd0, xrq2, P2[20].x, 8);
;                 DPPFMAC(yd1, xrq2, Q2[20].y, 9); DPPFMAC(zd1, xrq2, P2[20].y, 9);
;                 DPPFMAC(yd2, xrq2, Q2[21].x, 10); DPPFMAC(zd2, xrq2, P2[21].x, 10);
;                 DPPFMAC(yd3, xrq2, Q2[21].y, 11); DPPFMAC(zd3, xrq2, P2[21].y, 11);
;                 }
;                 { const f32x2 bxy = b_11.xy, bzw = b_11.zw;
;                 Q2[22] = Q2[22] * d_11.xy + (saq2 * bxy + vv2 * k_11.xy); Q2[23] = Q2[23] * d_11.zw + (saq2 * bzw + vv2 * k_11.zw);
	v_mfma_f32_4x4x1_16b_f32 v[96:99], v179, v232, v[96:99]
	v_mul_f32_e32 v100, v100, v217
	v_mul_f32_e32 v101, v101, v217
	v_mul_f32_e32 v102, v102, v217
	v_mul_f32_e32 v103, v103, v217
	v_mfma_f32_4x4x1_16b_f32 v[32:35], v254, v170, v[32:35]
	v_fmac_f32_e32 v246, v28, v199
	v_fmac_f32_e32 v250, v92, v199
	v_fmac_f32_e32 v247, v29, v199
	v_fmac_f32_e32 v251, v93, v199
	v_fmac_f32_e32 v248, v30, v199
	v_fmac_f32_e32 v252, v94, v199
	v_fmac_f32_e32 v249, v31, v199
	v_fmac_f32_e32 v253, v95, v199
	v_mfma_f32_4x4x1_16b_f32 v[36:39], v178, v233, v[36:39]
	v_mul_f32_e32 v40, v40, v218
	v_mul_f32_e32 v41, v41, v218
	v_mul_f32_e32 v42, v42, v218
	v_mul_f32_e32 v43, v43, v218
	v_mfma_f32_4x4x1_16b_f32 v[100:103], v179, v233, v[100:103]
	v_mul_f32_e32 v104, v104, v218
	v_mul_f32_e32 v105, v105, v218
	v_mul_f32_e32 v106, v106, v218
	v_mul_f32_e32 v107, v107, v218
	v_mfma_f32_4x4x1_16b_f32 v[36:39], v254, v171, v[36:39]
	v_fmac_f32_e32 v246, v32, v200
	v_fmac_f32_e32 v250, v96, v200
	v_fmac_f32_e32 v247, v33, v200
	v_fmac_f32_e32 v251, v97, v200
	v_fmac_f32_e32 v248, v34, v200
	v_fmac_f32_e32 v252, v98, v200
	v_fmac_f32_e32 v249, v35, v200
	v_fmac_f32_e32 v253, v99, v200
	v_mfma_f32_4x4x1_16b_f32 v[40:43], v178, v234, v[40:43]
	v_mul_f32_e32 v44, v44, v219
	v_mul_f32_e32 v45, v45, v219
	v_mul_f32_e32 v46, v46, v219
	v_mul_f32_e32 v47, v47, v219
	v_mfma_f32_4x4x1_16b_f32 v[104:107], v179, v234, v[104:107]
	v_mul_f32_e32 v108, v108, v219
	v_mul_f32_e32 v109, v109, v219
	v_mul_f32_e32 v110, v110, v219
	v_mul_f32_e32 v111, v111, v219
	v_mfma_f32_4x4x1_16b_f32 v[40:43], v254, v172, v[40:43]
	v_fmac_f32_e32 v246, v36, v201
	v_fmac_f32_e32 v250, v100, v201
	v_fmac_f32_e32 v247, v37, v201
	v_fmac_f32_e32 v251, v101, v201
	v_fmac_f32_e32 v248, v38, v201
	v_fmac_f32_e32 v252, v102, v201
	v_fmac_f32_e32 v249, v39, v201
	v_fmac_f32_e32 v253, v103, v201
	v_mfma_f32_4x4x1_16b_f32 v[44:47], v178, v235, v[44:47]
	v_mul_f32_e32 v48, v48, v220
	v_mul_f32_e32 v49, v49, v220
	v_mul_f32_e32 v50, v50, v220
	v_mul_f32_e32 v51, v51, v220
	v_mfma_f32_4x4x1_16b_f32 v[108:111], v179, v235, v[108:111]
	v_mul_f32_e32 v112, v112, v220
	v_mul_f32_e32 v113, v113, v220
	v_mul_f32_e32 v114, v114, v220
	v_mul_f32_e32 v115, v115, v220
	v_mfma_f32_4x4x1_16b_f32 v[44:47], v254, v173, v[44:47]
	v_fmac_f32_e32 v246, v40, v202
	v_fmac_f32_e32 v250, v104, v202
	v_fmac_f32_e32 v247, v41, v202
	v_fmac_f32_e32 v251, v105, v202
	v_fmac_f32_e32 v248, v42, v202
	v_fmac_f32_e32 v252, v106, v202
	v_fmac_f32_e32 v249, v43, v202
	v_fmac_f32_e32 v253, v107, v202
	v_mfma_f32_4x4x1_16b_f32 v[48:51], v178, v236, v[48:51]
	v_mul_f32_e32 v52, v52, v221
	v_mul_f32_e32 v53, v53, v221
	v_mul_f32_e32 v54, v54, v221
	v_mul_f32_e32 v55, v55, v221
	v_mfma_f32_4x4x1_16b_f32 v[112:115], v179, v236, v[112:115]
	v_mul_f32_e32 v116, v116, v221
	v_mul_f32_e32 v117, v117, v221
	v_mul_f32_e32 v118, v118, v221
	v_mul_f32_e32 v119, v119, v221
	v_mfma_f32_4x4x1_16b_f32 v[48:51], v254, v174, v[48:51]
	v_fmac_f32_e32 v246, v44, v203
	v_fmac_f32_e32 v250, v108, v203
	v_fmac_f32_e32 v247, v45, v203
	v_fmac_f32_e32 v251, v109, v203
	v_fmac_f32_e32 v248, v46, v203
	v_fmac_f32_e32 v252, v110, v203
	v_fmac_f32_e32 v249, v47, v203
	v_fmac_f32_e32 v253, v111, v203
	v_mfma_f32_4x4x1_16b_f32 v[52:55], v178, v237, v[52:55]
	v_mul_f32_e32 v56, v56, v222
	v_mul_f32_e32 v57, v57, v222
	v_mul_f32_e32 v58, v58, v222
	v_mul_f32_e32 v59, v59, v222
	v_mfma_f32_4x4x1_16b_f32 v[116:119], v179, v237, v[116:119]
	v_mul_f32_e32 v120, v120, v222
	v_mul_f32_e32 v121, v121, v222
	v_mul_f32_e32 v122, v122, v222
	v_mul_f32_e32 v123, v123, v222
	v_mfma_f32_4x4x1_16b_f32 v[52:55], v254, v175, v[52:55]
	v_fmac_f32_e32 v246, v48, v204
	v_fmac_f32_e32 v250, v112, v204
	v_fmac_f32_e32 v247, v49, v204
	v_fmac_f32_e32 v251, v113, v204
	v_fmac_f32_e32 v248, v50, v204
	v_fmac_f32_e32 v252, v114, v204
	v_fmac_f32_e32 v249, v51, v204
	v_fmac_f32_e32 v253, v115, v204
	v_mfma_f32_4x4x1_16b_f32 v[56:59], v178, v238, v[56:59]
	v_mul_f32_e32 v60, v60, v223
	v_mul_f32_e32 v61, v61, v223
	v_mul_f32_e32 v62, v62, v223
	v_mul_f32_e32 v63, v63, v223
	v_mfma_f32_4x4x1_16b_f32 v[120:123], v179, v238, v[120:123]
	v_mul_f32_e32 v124, v124, v223
	v_mul_f32_e32 v125, v125, v223
	v_mul_f32_e32 v126, v126, v223
	v_mul_f32_e32 v127, v127, v223
	v_mfma_f32_4x4x1_16b_f32 v[56:59], v254, v176, v[56:59]
	v_fmac_f32_e32 v246, v52, v205
	v_fmac_f32_e32 v250, v116, v205
	v_fmac_f32_e32 v247, v53, v205
	v_fmac_f32_e32 v251, v117, v205
	v_fmac_f32_e32 v248, v54, v205
	v_fmac_f32_e32 v252, v118, v205
	v_fmac_f32_e32 v249, v55, v205
	v_fmac_f32_e32 v253, v119, v205
	v_mfma_f32_4x4x1_16b_f32 v[60:63], v178, v239, v[60:63]
	v_mfma_f32_4x4x1_16b_f32 v[124:127], v179, v239, v[124:127]
	v_fmac_f32_e32 v246, v56, v206
	v_fmac_f32_e32 v250, v120, v206
	v_fmac_f32_e32 v247, v57, v206
	v_fmac_f32_e32 v251, v121, v206
	v_mfma_f32_4x4x1_16b_f32 v[60:63], v254, v177, v[60:63]
	v_fmac_f32_e32 v248, v58, v206
; __device__ __forceinline__ unsigned f2bf(float f) { unsigned u = __float_as_uint(f); return (u + 0x7fffu + ((u >> 16) & 1u)) >> 16; }
; #define DPPFMAC(acc, rep, val, n) asm("v_fmac_f32_dpp %0, %1, %2 row_newbcast:" #n " row_mask:0xf bank_mask:0xf" : "+v"(acc) : "v"(rep), "v"(val))
;     ...
;                 { const f32x2 bxy = b_14.xy, bzw = b_14.zw;
;                 Q2[28] = Q2[28] * d_14.xy + (saq2 * bxy + vv2 * k_14.xy); Q2[29] = Q2[29] * d_14.zw + (saq2 * bzw + vv2 * k_14.zw);
;                 P2[28] = P2[28] * d_14.xy + sap2 * bxy; P2[29] = P2[29] * d_14.zw + sap2 * bzw;
;                 DPPFMAC(yd0, xrq3, Q2[28].x, 8); DPPFMAC(zd0, xrq3, P2[28].x, 8);
;                 DPPFMAC(yd1, xrq3, Q2[28].y, 9); DPPFMAC(zd1, xrq3, P2[28].y, 9);
;                 DPPFMAC(yd2, xrq3, Q2[29].x, 10); DPPFMAC(zd2, xrq3, P2[29].x, 10);
;                 DPPFMAC(yd3, xrq3, Q2[29].y, 11); DPPFMAC(zd3, xrq3, P2[29].y, 11);
;                 }
;                 { const f32x2 bxy = b_15.xy, bzw = b_15.zw;
;                 Q2[30] = Q2[30] * d_15.xy + (saq2 * bxy + vv2 * k_15.xy); Q2[31] = Q2[31] * d_15.zw + (saq2 * bzw + vv2 * k_15.zw);
;                 P2[30] = P2[30] * d_15.xy + sap2 * bxy; P2[31] = P2[31] * d_15.zw + sap2 * bzw;
;                 DPPFMAC(yd0, xrq3, Q2[30].x, 12); DPPFMAC(zd0, xrq3, P2[30].x, 12);
;                 DPPFMAC(yd1, xrq3, Q2[30].y, 13); DPPFMAC(zd1, xrq3, P2[30].y, 13);
;                 DPPFMAC(yd2, xrq3, Q2[31].x, 14); DPPFMAC(zd2, xrq3, P2[31].x, 14);
;                 DPPFMAC(yd3, xrq3, Q2[31].y, 15); DPPFMAC(zd3, xrq3, P2[31].y, 15);
;                 }
;                 __builtin_amdgcn_sched_barrier(0);
;                 }
;                 if (!PASS2 && MODE == 0) {
;                     const unsigned ox = i0 + (unsigned)((seg * SB + s) * DB);
;                     YT[ox] = (yd0 + yd1) + (yd2 + yd3); ZT[ox] = (bf16)f2bf((zd0 + zd1) + (zd2 + zd3));
	v_fmac_f32_e32 v252, v122, v206
	v_fmac_f32_e32 v249, v59, v206
	v_fmac_f32_e32 v253, v123, v206
	v_fmac_f32_e32 v246, v60, v207
	v_fmac_f32_e32 v250, v124, v207
	v_fmac_f32_e32 v247, v61, v207
	v_fmac_f32_e32 v251, v125, v207
	v_fmac_f32_e32 v248, v62, v207
	v_fmac_f32_e32 v252, v126, v207
	v_fmac_f32_e32 v249, v63, v207
	v_fmac_f32_e32 v253, v127, v207
	v_add_f32_dpp v246, v246, v246 quad_perm:[1,0,3,2] row_mask:0xf bank_mask:0xf
	v_add_f32_dpp v247, v247, v247 quad_perm:[1,0,3,2] row_mask:0xf bank_mask:0xf
	v_add_f32_dpp v248, v248, v248 quad_perm:[1,0,3,2] row_mask:0xf bank_mask:0xf
	v_add_f32_dpp v249, v249, v249 quad_perm:[1,0,3,2] row_mask:0xf bank_mask:0xf
	v_add_f32_dpp v250, v250, v250 quad_perm:[1,0,3,2] row_mask:0xf bank_mask:0xf
	v_add_f32_dpp v251, v251, v251 quad_perm:[1,0,3,2] row_mask:0xf bank_mask:0xf
	v_add_f32_dpp v252, v252, v252 quad_perm:[1,0,3,2] row_mask:0xf bank_mask:0xf
	v_add_f32_dpp v253, v253, v253 quad_perm:[1,0,3,2] row_mask:0xf bank_mask:0xf
	v_add_f32_dpp v246, v246, v246 quad_perm:[2,3,0,1] row_mask:0xf bank_mask:0xf
	v_add_f32_dpp v247, v247, v247 quad_perm:[2,3,0,1] row_mask:0xf bank_mask:0xf
	v_add_f32_dpp v248, v248, v248 quad_perm:[2,3,0,1] row_mask:0xf bank_mask:0xf
	v_add_f32_dpp v249, v249, v249 quad_perm:[2,3,0,1] row_mask:0xf bank_mask:0xf
	v_add_f32_dpp v250, v250, v250 quad_perm:[2,3,0,1] row_mask:0xf bank_mask:0xf
	v_add_f32_dpp v251, v251, v251 quad_perm:[2,3,0,1] row_mask:0xf bank_mask:0xf
	v_add_f32_dpp v252, v252, v252 quad_perm:[2,3,0,1] row_mask:0xf bank_mask:0xf
	v_add_f32_dpp v253, v253, v253 quad_perm:[2,3,0,1] row_mask:0xf bank_mask:0xf
	v_cndmask_b32_e64 v178, v246, v247, s[98:99]
	v_cndmask_b32_e64 v179, v250, v251, s[98:99]
	v_cndmask_b32_e64 v178, v178, v248, s[100:101]
	v_cndmask_b32_e64 v179, v179, v252, s[100:101]
	v_cndmask_b32_e64 v178, v178, v249, s[84:85]
	v_cndmask_b32_e64 v179, v179, v253, s[84:85]
	v_add_u32_e32 v130, s45, v141
	v_lshl_add_u64 v[166:167], v[130:131], 2, s[26:27]
	v_lshl_add_u64 v[168:169], v[130:131], 1, s[12:13]
	v_bfe_u32 v130, v179, 16, 1
	v_add3_u32 v130, v179, v130, s41
	s_addk_i32 s45, 0x400
	v_add_u32_e32 v158, 0x600, v158
	global_store_dword v[166:167], v178, off
	global_store_short_d16_hi v[168:169], v130, off
	s_cmpk_eq_i32 s45, 0x1000
	s_cbranch_scc0 .Lp5_step
	s_andn2_b64 vcc, exec, s[66:67]
	s_cbranch_vccnz .LBB0_1077
	v_sub_f32_e32 v157, v157, v142
	v_sub_f32_e32 v130, v159, v143
	v_fma_f32 v157, v183, v157, v142
	v_add_f32_e32 v159, -1.0, v146
	v_mul_f32_e32 v158, v185, v157
	v_fma_f32 v159, v186, v159, 1.0
	v_fma_f32 v130, v182, v130, v143
	v_mul_f32_e32 v157, v159, v157
	v_mul_f32_e32 v159, v158, v158
	v_mul_f32_e32 v165, v130, v157
	v_mul_f32_e32 v166, v187, v165
	v_mov_b32_dpp v159, v159 row_shr:1 row_mask:0xf bank_mask:0xf bound_ctrl:1
	v_fmac_f32_e32 v159, v158, v158
	v_mov_b32_dpp v166, v166 row_shr:1 row_mask:0xf bank_mask:0xf bound_ctrl:1
	v_fmac_f32_e32 v166, v187, v165
	v_add_f32_dpp v159, v159, v159 row_shr:2 row_mask:0xf bank_mask:0xf bound_ctrl:1
	s_lshl_b32 s43, s43, 2
	v_add_f32_dpp v165, v166, v166 row_shr:2 row_mask:0xf bank_mask:0xf bound_ctrl:1
	v_add_f32_dpp v159, v159, v159 row_shr:4 row_mask:0xf bank_mask:0xf bound_ctrl:1
	v_mov_b32_e32 v166, v131
	v_add_f32_dpp v165, v165, v165 row_shr:4 row_mask:0xf bank_mask:0xf bound_ctrl:1
	v_add_f32_dpp v159, v159, v159 row_shr:8 row_mask:0xf bank_mask:0xf bound_ctrl:1
	s_and_b32 s43, s43, 4
	v_add_f32_dpp v165, v165, v165 row_shr:8 row_mask:0xf bank_mask:0xf bound_ctrl:1
	v_mov_b32_dpp v166, v159 row_bcast:15 row_mask:0xa bank_mask:0xf
	v_add_f32_e32 v159, v159, v166
	v_mov_b32_e32 v166, v131
	s_xor_b32 s46, s43, 4
	s_mulk_i32 s46, 0x600
	v_mov_b32_dpp v166, v165 row_bcast:15 row_mask:0xa bank_mask:0xf
	v_add_f32_e32 v165, v165, v166
	v_mov_b32_e32 v166, v131
	v_sub_f32_e32 v156, v156, v133
	v_fma_f32 v156, v184, v156, v133
	v_mov_b32_dpp v166, v159 row_bcast:31 row_mask:0xc bank_mask:0xf
	v_add_f32_e32 v159, v159, v166
	v_mov_b32_e32 v166, v131
	v_readlane_b32 s45, v159, 63
	s_nop 0
	v_mov_b32_dpp v166, v165 row_bcast:31 row_mask:0xc bank_mask:0xf
	v_max_f32_e64 v159, s45, s45
	v_max_f32_e32 v159, 0x179abe15, v159
	v_rsq_f32_e32 v159, v159
	v_add_f32_e32 v165, v165, v166
	v_mul_f32_e32 v158, v158, v159
	v_add_u32_e32 v159, s46, v180
	ds_write2st64_b32 v159, v189, v158 offset1:1
	v_mul_f32_e32 v158, v146, v158
	v_readlane_b32 s45, v165, 63
	ds_write2st64_b32 v159, v158, v157 offset0:2 offset1:3
	ds_write2st64_b32 v159, v156, v130 offset0:4 offset1:5
	v_bfe_u32 v130, v156, 16, 1
	v_mov_b32_e32 v165, v131
	v_add3_u32 v130, v156, v130, s41
	v_lshl_add_u64 v[156:157], v[164:165], 1, s[18:19]
	global_store_short_d16_hi v[156:157], v130, off
	s_and_saveexec_b64 s[66:67], s[4:5]
	s_cbranch_execz .LBB0_1070
	v_lshl_add_u32 v130, s44, 6, v140
	v_lshl_add_u64 v[156:157], v[130:131], 2, s[36:37]
	v_mov_b32_e32 v130, s45
	global_store_dword v[156:157], v130, off

; __global__ void __launch_bounds__(NTHR, 2) fwd_kernel(Params p) {
	.amdhsa_kernel _Z10fwd_kernel6Params
		.amdhsa_group_segment_fixed_size 0
		.amdhsa_private_segment_fixed_size 0
		.amdhsa_kernarg_size 496
		.amdhsa_user_sgpr_count 2
		.amdhsa_user_sgpr_dispatch_ptr 0
		.amdhsa_user_sgpr_queue_ptr 0
		.amdhsa_user_sgpr_kernarg_segment_ptr 1
		.amdhsa_user_sgpr_dispatch_id 0
		.amdhsa_user_sgpr_kernarg_preload_length 0
		.amdhsa_user_sgpr_kernarg_preload_offset 0
		.amdhsa_user_sgpr_private_segment_size 0
		.amdhsa_uses_dynamic_stack 0
		.amdhsa_enable_private_segment 0
		.amdhsa_system_sgpr_workgroup_id_x 1
		.amdhsa_system_sgpr_workgroup_id_y 0
		.amdhsa_system_sgpr_workgroup_id_z 0
		.amdhsa_system_sgpr_workgroup_info 0
		.amdhsa_system_vgpr_workitem_id 2
		.amdhsa_next_free_vgpr 256
		.amdhsa_next_free_sgpr 102
		.amdhsa_accum_offset 256
		.amdhsa_reserve_vcc 1
		.amdhsa_float_round_mode_32 0
		.amdhsa_float_round_mode_16_64 0
		.amdhsa_float_denorm_mode_32 3
		.amdhsa_float_denorm_mode_16_64 3
		.amdhsa_dx10_clamp 1
		.amdhsa_ieee_mode 1
		.amdhsa_fp16_overflow 0
		.amdhsa_tg_split 0
		.amdhsa_exception_fp_ieee_invalid_op 0
		.amdhsa_exception_fp_denorm_src 0
		.amdhsa_exception_fp_ieee_div_zero 0
		.amdhsa_exception_fp_ieee_overflow 0
		.amdhsa_exception_fp_ieee_underflow 0
		.amdhsa_exception_fp_ieee_inexact 0
		.amdhsa_exception_int_div_zero 0
	.end_amdhsa_kernel

; __global__ void __launch_bounds__(NTHR, 2) fwd_kernel(Params p) {
amdhsa.kernels:
  - .agpr_count:     0
    .args:
      - .offset:         0
        .size:           240
        .value_kind:     by_value
      - .offset:         240
        .size:           4
        .value_kind:     hidden_block_count_x
      - .offset:         244
        .size:           4
        .value_kind:     hidden_block_count_y
      - .offset:         248
        .size:           4
        .value_kind:     hidden_block_count_z
      - .offset:         252
        .size:           2
        .value_kind:     hidden_group_size_x
      - .offset:         254
        .size:           2
        .value_kind:     hidden_group_size_y
      - .offset:         256
        .size:           2
        .value_kind:     hidden_group_size_z
      - .offset:         258
        .size:           2
        .value_kind:     hidden_remainder_x
      - .offset:         260
        .size:           2
        .value_kind:     hidden_remainder_y
      - .offset:         262
        .size:           2
        .value_kind:     hidden_remainder_z
      - .offset:         280
        .size:           8
        .value_kind:     hidden_global_offset_x
      - .offset:         288
        .size:           8
        .value_kind:     hidden_global_offset_y
      - .offset:         296
        .size:           8
        .value_kind:     hidden_global_offset_z
      - .offset:         304
        .size:           2
        .value_kind:     hidden_grid_dims
      - .offset:         328
        .size:           8
        .value_kind:     hidden_multigrid_sync_arg
      - .offset:         360
        .size:           4
        .value_kind:     hidden_dynamic_lds_size
    .group_segment_fixed_size: 0
    .kernarg_segment_align: 8
    .kernarg_segment_size: 496
    .language:       OpenCL C
    .language_version:
      - 2
      - 0
    .max_flat_workgroup_size: 512
    .name:           _Z10fwd_kernel6Params
    .private_segment_fixed_size: 0
    .sgpr_count:     108
    .sgpr_spill_count: 70
    .symbol:         _Z10fwd_kernel6Params.kd
    .uniform_work_group_size: 1
    .uses_dynamic_stack: false
    .vgpr_count:     256
    .vgpr_spill_count: 0
    .wavefront_size: 64
